# combo9 + E35/E36: phase 1 only produces u for slab 0; u of slab b+1 is produced inside slab b's in-proj phase by the CUs that idle in its last tile round (pipelined row loop)
# baseline (speedup 1.0000x reference)
.LBB0_11:
	s_mov_b64 s[10:11], -1
	s_mov_b64 s[0:1], 0
	s_cmp_lt_i32 s6, 1
	s_mov_b64 s[8:9], 0
	s_mov_b64 s[12:13], 0
	s_cbranch_scc1 .LBB0_17
	s_mov_b64 s[12:13], -1
	s_mov_b64 s[10:11], 0
	s_cmp_eq_u32 s6, 1
	s_cbranch_scc0 .LBB0_17
	v_mov_b32_e32 v0, v167
	v_readlane_b32 s9, v251, 14
	v_readfirstlane_b32 s8, v0
	s_ashr_i32 s8, s8, 6
	s_add_i32 s8, s8, s9
	s_movk_i32 s3, 0x7fff
	s_cmpk_lg_u32 s36, 0x100
	s_cbranch_scc1 .Lp1_bnd
	s_movk_i32 s3, 0x1fff
.Lp1_bnd:
	s_cmp_gt_i32 s8, s3
	s_cbranch_scc1 .LBB0_16
	v_cmp_lt_i32_e32 vcc, v188, v187
	v_and_b32_e32 v4, 63, v0
	v_readlane_b32 s84, v254, 4
	v_cndmask_b32_e32 v2, v185, v188, vcc
	v_cmp_lt_i32_e32 vcc, v189, v187
	v_lshlrev_b32_e32 v6, 2, v2
	v_lshlrev_b32_e32 v156, 4, v4
	v_cndmask_b32_e32 v2, v185, v189, vcc
	v_cmp_lt_i32_e32 vcc, v190, v187
	v_lshlrev_b32_e32 v7, 2, v2
	v_readlane_b32 s85, v254, 5
	v_cndmask_b32_e32 v2, v185, v190, vcc
	v_cmp_lt_i32_e32 vcc, v191, v187
	s_waitcnt vmcnt(0)
	v_lshlrev_b32_e32 v8, 2, v2
	v_readlane_b32 s88, v254, 8
	v_cndmask_b32_e32 v2, v185, v191, vcc
	v_cmp_lt_i32_e32 vcc, v250, v187
	v_lshlrev_b32_e32 v9, 2, v2
	v_readlane_b32 s89, v254, 9
	v_cndmask_b32_e32 v2, v185, v250, vcc
	v_cmp_lt_i32_e32 vcc, v184, v187
	v_lshlrev_b32_e32 v10, 2, v2
	v_lshlrev_b32_e32 v12, 2, v4
	v_cndmask_b32_e32 v2, v185, v184, vcc
	v_readlane_b32 s12, v251, 12
	s_waitcnt lgkmcnt(0)
	v_lshl_add_u64 v[0:1], s[84:85], 0, v[156:157]
	v_lshlrev_b32_e32 v11, 2, v2
	v_lshl_add_u64 v[2:3], s[88:89], 0, v[156:157]
	v_or_b32_e32 v14, 0x100, v12
	v_or_b32_e32 v16, 0x200, v12
	v_or_b32_e32 v18, 0x300, v12
	v_lshlrev_b32_e32 v156, 3, v4
	v_readlane_b32 s13, v251, 13
	v_lshlrev_b32_e32 v12, 2, v12
	v_lshlrev_b32_e32 v13, 2, v14
	v_lshl_add_u64 v[4:5], s[12:13], 0, v[156:157]
	v_lshlrev_b32_e32 v14, 2, v16
	v_lshlrev_b32_e32 v15, 2, v18
	v_readlane_b32 s86, v254, 6
	v_readlane_b32 s87, v254, 7
	v_readlane_b32 s90, v254, 10
	v_readlane_b32 s91, v254, 11
	v_readlane_b32 s92, v254, 12
	v_readlane_b32 s93, v254, 13
	v_readlane_b32 s94, v254, 14
	v_readlane_b32 s95, v254, 15
	v_readlane_b32 s96, v254, 16
	v_readlane_b32 s97, v254, 17
	v_readlane_b32 s98, v254, 18
	v_readlane_b32 s99, v254, 19
.LBB0_15:
	s_ashr_i32 s9, s8, 31
	s_lshl_b64 s[12:13], s[8:9], 12
	v_lshl_add_u64 v[28:29], v[0:1], 0, s[12:13]
	global_load_dwordx4 v[16:19], v[28:29], off
	global_load_dwordx4 v[20:23], v[28:29], off offset:1024
	global_load_dwordx4 v[24:27], v[28:29], off offset:2048
	s_nop 0
	global_load_dwordx4 v[28:31], v[28:29], off offset:3072
	s_lshr_b32 s12, s9, 19
	s_add_i32 s12, s8, s12
	s_ashr_i32 s12, s12, 13
	s_mulk_i32 s12, 0xc00
	s_ashr_i32 s13, s12, 31
	s_lshl_b64 s[12:13], s[12:13], 2
	s_add_u32 s12, s58, s12
	s_addc_u32 s13, s59, s13
	s_add_u32 s14, s12, 0x1000
	s_addc_u32 s15, s13, 0
	global_load_dwordx4 v[32:35], v12, s[14:15]
	global_load_dwordx4 v[36:39], v[2:3], off
	global_load_dwordx4 v[40:43], v12, s[12:13]
	s_lshl_b64 s[16:17], s[8:9], 11
	s_add_i32 s8, s8, s33
	s_cmp_gt_i32 s8, s3
	s_waitcnt vmcnt(6)
	v_mov_b32_e32 v46, v17
	s_waitcnt vmcnt(5)
	v_mov_b32_e32 v47, v21
	v_mov_b32_e32 v44, v16
	v_mov_b32_e32 v45, v20
	s_waitcnt vmcnt(4)
	v_mov_b32_e32 v54, v25
	s_waitcnt vmcnt(3)
	v_mov_b32_e32 v55, v29
	v_pk_mul_f32 v[46:47], v[46:47], v[46:47]
	v_mov_b32_e32 v48, v18
	v_mov_b32_e32 v49, v22
	v_mov_b32_e32 v52, v24
	v_mov_b32_e32 v53, v28
	v_pk_mul_f32 v[54:55], v[54:55], v[54:55]
	v_pk_fma_f32 v[44:45], v[44:45], v[44:45], v[46:47]
	v_mov_b32_e32 v50, v19
	v_mov_b32_e32 v51, v23
	v_mov_b32_e32 v56, v26
	v_mov_b32_e32 v57, v30
	v_pk_fma_f32 v[46:47], v[52:53], v[52:53], v[54:55]
	v_pk_fma_f32 v[44:45], v[48:49], v[48:49], v[44:45]
	v_mov_b32_e32 v58, v27
	v_mov_b32_e32 v59, v31
	v_pk_fma_f32 v[46:47], v[56:57], v[56:57], v[46:47]
	v_pk_fma_f32 v[44:45], v[50:51], v[50:51], v[44:45]
	v_pk_fma_f32 v[46:47], v[58:59], v[58:59], v[46:47]
	v_add_f32_e32 v44, v44, v45
	v_add_f32_e32 v44, v44, v46
	v_add_f32_e32 v44, v44, v47
	ds_bpermute_b32 v45, v6, v44
	s_waitcnt vmcnt(2)
	v_add_f32_e32 v32, 1.0, v32
	v_add_f32_e32 v33, 1.0, v33
	v_add_f32_e32 v34, 1.0, v34
	v_add_f32_e32 v35, 1.0, v35
	s_waitcnt lgkmcnt(0)
	v_add_f32_e32 v44, v44, v45
	ds_bpermute_b32 v45, v7, v44
	s_waitcnt lgkmcnt(0)
	v_add_f32_e32 v44, v44, v45
	ds_bpermute_b32 v45, v8, v44
	s_waitcnt lgkmcnt(0)
	v_add_f32_e32 v44, v44, v45
	ds_bpermute_b32 v45, v9, v44
	s_waitcnt lgkmcnt(0)
	v_add_f32_e32 v44, v44, v45
	ds_bpermute_b32 v45, v10, v44
	s_waitcnt lgkmcnt(0)
	v_add_f32_e32 v46, v44, v45
	ds_bpermute_b32 v47, v11, v46
	v_lshl_add_u64 v[44:45], v[4:5], 0, s[16:17]
	s_waitcnt lgkmcnt(0)
	v_add_f32_e32 v46, v46, v47
	v_fmamk_f32 v46, v46, 0x3a800000, v182
	v_mul_f32_e32 v47, 0x4b800000, v46
	v_cmp_gt_f32_e32 vcc, s56, v46
	s_nop 1
	v_cndmask_b32_e32 v46, v46, v47, vcc
	v_rsq_f32_e32 v46, v46
	s_nop 0
	v_mul_f32_e32 v47, 0x45800000, v46
	v_cndmask_b32_e32 v46, v46, v47, vcc
	v_mul_f32_e32 v16, v16, v46
	v_mul_f32_e32 v17, v17, v46
	v_mul_f32_e32 v18, v18, v46
	v_mul_f32_e32 v19, v19, v46
	s_waitcnt vmcnt(1)
	v_mul_f32_e32 v16, v36, v16
	v_mul_f32_e32 v17, v37, v17
	v_mul_f32_e32 v18, v38, v18
	v_mul_f32_e32 v19, v39, v19
	s_waitcnt vmcnt(0)
	v_fma_f32 v16, v32, v16, v40
	v_fma_f32 v17, v33, v17, v41
	v_fma_f32 v18, v34, v18, v42
	v_fmac_f32_e32 v43, v19, v35
	v_cvt_pk_bf16_f32 v16, v16, v17
	v_cvt_pk_bf16_f32 v17, v18, v43
	global_store_dwordx2 v[44:45], v[16:17], off
	global_load_dwordx4 v[16:19], v[2:3], off offset:1024
	s_nop 0
	global_load_dwordx4 v[32:35], v13, s[14:15]
	global_load_dwordx4 v[36:39], v12, s[12:13] offset:1024
	v_mul_f32_e32 v20, v20, v46
	v_mul_f32_e32 v21, v21, v46
	v_mul_f32_e32 v22, v22, v46
	v_mul_f32_e32 v23, v23, v46
	v_mul_f32_e32 v24, v24, v46
	v_mul_f32_e32 v25, v25, v46
	v_mul_f32_e32 v26, v26, v46
	v_mul_f32_e32 v27, v27, v46
	v_mul_f32_e32 v28, v28, v46
	v_mul_f32_e32 v29, v29, v46
	v_mul_f32_e32 v30, v30, v46
	v_mul_f32_e32 v31, v31, v46
	s_waitcnt vmcnt(2)
	v_mul_f32_e32 v16, v20, v16
	s_waitcnt vmcnt(1)
	v_add_f32_e32 v20, 1.0, v32
	v_mul_f32_e32 v17, v21, v17
	v_add_f32_e32 v21, 1.0, v33
	v_mul_f32_e32 v18, v22, v18
	v_add_f32_e32 v22, 1.0, v34
	v_mul_f32_e32 v19, v23, v19
	v_add_f32_e32 v23, 1.0, v35
	s_waitcnt vmcnt(0)
	v_fma_f32 v16, v16, v20, v36
	v_fma_f32 v17, v17, v21, v37
	v_fma_f32 v18, v18, v22, v38
	v_fmac_f32_e32 v39, v19, v23
	v_cvt_pk_bf16_f32 v16, v16, v17
	v_cvt_pk_bf16_f32 v17, v18, v39
	global_store_dwordx2 v[44:45], v[16:17], off offset:512
	global_load_dwordx4 v[16:19], v[2:3], off offset:2048
	s_nop 0
	global_load_dwordx4 v[20:23], v14, s[14:15]
	global_load_dwordx4 v[32:35], v12, s[12:13] offset:2048
	s_waitcnt vmcnt(2)
	v_mul_f32_e32 v16, v24, v16
	s_waitcnt vmcnt(1)
	v_add_f32_e32 v20, 1.0, v20
	v_mul_f32_e32 v17, v25, v17
	v_add_f32_e32 v21, 1.0, v21
	v_mul_f32_e32 v18, v26, v18
	v_add_f32_e32 v22, 1.0, v22
	v_mul_f32_e32 v19, v27, v19
	v_add_f32_e32 v23, 1.0, v23
	s_waitcnt vmcnt(0)
	v_fma_f32 v16, v16, v20, v32
	v_fma_f32 v17, v17, v21, v33
	v_fma_f32 v18, v18, v22, v34
	v_fmac_f32_e32 v35, v19, v23
	v_cvt_pk_bf16_f32 v16, v16, v17
	v_cvt_pk_bf16_f32 v17, v18, v35
	global_store_dwordx2 v[44:45], v[16:17], off offset:1024
	global_load_dwordx4 v[16:19], v[2:3], off offset:3072
	s_nop 0
	global_load_dwordx4 v[20:23], v15, s[14:15]
	global_load_dwordx4 v[24:27], v12, s[12:13] offset:3072
	s_waitcnt vmcnt(2)
	v_mul_f32_e32 v16, v28, v16
	s_waitcnt vmcnt(1)
	v_add_f32_e32 v20, 1.0, v20
	v_mul_f32_e32 v17, v29, v17
	v_add_f32_e32 v21, 1.0, v21
	v_mul_f32_e32 v18, v30, v18
	v_add_f32_e32 v22, 1.0, v22
	v_mul_f32_e32 v19, v31, v19
	v_add_f32_e32 v23, 1.0, v23
	s_waitcnt vmcnt(0)
	v_fma_f32 v16, v16, v20, v24
	v_fma_f32 v17, v17, v21, v25
	v_fma_f32 v18, v18, v22, v26
	v_fmac_f32_e32 v27, v19, v23
	v_cvt_pk_bf16_f32 v16, v16, v17
	v_cvt_pk_bf16_f32 v17, v18, v27
	global_store_dwordx2 v[44:45], v[16:17], off offset:1536
	s_cbranch_scc0 .LBB0_15

.Ldpg_skip:
	s_cmpk_lg_u32 s36, 0x100
	s_cbranch_scc1 .Ldp1_skip
	s_cmpk_lt_u32 s57, 0xa0
	s_cbranch_scc1 .Ldp1_skip
	v_readlane_b32 s10, v254, 62
	s_nop 3
	s_cmp_gt_u32 s10, 2
	s_cbranch_scc1 .Ldp1_skip
	v_mov_b32_e32 v0, v167
	v_readlane_b32 s9, v251, 14
	v_readfirstlane_b32 s8, v0
	s_ashr_i32 s8, s8, 6
	s_add_i32 s8, s8, s9
	s_add_i32 s8, s8, 0xfffffb00
	s_add_i32 s10, s10, 1
	s_lshl_b32 s10, s10, 13
	s_add_i32 s8, s8, s10
	s_add_i32 s18, s10, 0x1fff
	s_mov_b32 s56, 0x800000
	v_readlane_b32 s58, v254, 37
	v_readlane_b32 s59, v254, 38
	v_cmp_lt_i32_e32 vcc, v188, v187
	v_and_b32_e32 v4, 63, v0
	v_readlane_b32 s84, v254, 4
	v_cndmask_b32_e32 v2, v185, v188, vcc
	v_cmp_lt_i32_e32 vcc, v189, v187
	v_lshlrev_b32_e32 v6, 2, v2
	v_lshlrev_b32_e32 v156, 4, v4
	v_cndmask_b32_e32 v2, v185, v189, vcc
	v_cmp_lt_i32_e32 vcc, v190, v187
	v_lshlrev_b32_e32 v7, 2, v2
	v_readlane_b32 s85, v254, 5
	v_cndmask_b32_e32 v2, v185, v190, vcc
	v_cmp_lt_i32_e32 vcc, v191, v187
	s_waitcnt vmcnt(0)
	v_lshlrev_b32_e32 v8, 2, v2
	v_readlane_b32 s88, v254, 8
	v_cndmask_b32_e32 v2, v185, v191, vcc
	v_cmp_lt_i32_e32 vcc, v250, v187
	v_lshlrev_b32_e32 v9, 2, v2
	v_readlane_b32 s89, v254, 9
	v_cndmask_b32_e32 v2, v185, v250, vcc
	v_cmp_lt_i32_e32 vcc, v184, v187
	v_lshlrev_b32_e32 v10, 2, v2
	v_lshlrev_b32_e32 v12, 2, v4
	v_cndmask_b32_e32 v2, v185, v184, vcc
	v_readlane_b32 s12, v251, 12
	s_waitcnt lgkmcnt(0)
	v_lshl_add_u64 v[0:1], s[84:85], 0, v[156:157]
	v_lshlrev_b32_e32 v11, 2, v2
	v_lshl_add_u64 v[2:3], s[88:89], 0, v[156:157]
	v_or_b32_e32 v14, 0x100, v12
	v_or_b32_e32 v16, 0x200, v12
	v_or_b32_e32 v18, 0x300, v12
	v_lshlrev_b32_e32 v156, 3, v4
	v_readlane_b32 s13, v251, 13
	v_lshlrev_b32_e32 v12, 2, v12
	v_lshlrev_b32_e32 v13, 2, v14
	v_lshl_add_u64 v[4:5], s[12:13], 0, v[156:157]
	v_lshlrev_b32_e32 v14, 2, v16
	v_lshlrev_b32_e32 v15, 2, v18
	v_readlane_b32 s86, v254, 6
	v_readlane_b32 s87, v254, 7
	v_readlane_b32 s90, v254, 10
	v_readlane_b32 s91, v254, 11
	v_readlane_b32 s92, v254, 12
	v_readlane_b32 s93, v254, 13
	v_readlane_b32 s94, v254, 14
	v_readlane_b32 s95, v254, 15
	v_readlane_b32 s96, v254, 16
	v_readlane_b32 s97, v254, 17
	v_readlane_b32 s98, v254, 18
	v_readlane_b32 s99, v254, 19
	s_ashr_i32 s9, s8, 31
	s_lshl_b64 s[12:13], s[8:9], 12
	v_lshl_add_u64 v[124:125], v[0:1], 0, s[12:13]
	global_load_dwordx4 v[60:63], v[124:125], off
	global_load_dwordx4 v[64:67], v[124:125], off offset:1024
	global_load_dwordx4 v[68:71], v[124:125], off offset:2048
	global_load_dwordx4 v[72:75], v[124:125], off offset:3072
	global_load_dwordx4 v[108:111], v[2:3], off
	global_load_dwordx4 v[112:115], v[2:3], off offset:1024
	global_load_dwordx4 v[116:119], v[2:3], off offset:2048
	global_load_dwordx4 v[120:123], v[2:3], off offset:3072
.Ldp1_loop:
	s_ashr_i32 s9, s8, 31
	s_lshr_b32 s12, s9, 19
	s_add_i32 s12, s8, s12
	s_ashr_i32 s12, s12, 13
	s_mulk_i32 s12, 0xc00
	s_ashr_i32 s13, s12, 31
	s_lshl_b64 s[12:13], s[12:13], 2
	s_add_u32 s12, s58, s12
	s_addc_u32 s13, s59, s13
	s_add_u32 s14, s12, 0x1000
	s_addc_u32 s15, s13, 0
	s_lshl_b64 s[16:17], s[8:9], 11
	s_add_i32 s32, s8, 0x300
	s_cmp_gt_i32 s32, s18
	s_cselect_b32 s2, s8, s32
	s_ashr_i32 s3, s2, 31
	s_lshl_b64 s[2:3], s[2:3], 12
	s_waitcnt vmcnt(4)
	v_mov_b32_e32 v16, v60
	v_mov_b32_e32 v17, v61
	v_mov_b32_e32 v18, v62
	v_mov_b32_e32 v19, v63
	v_mov_b32_e32 v20, v64
	v_mov_b32_e32 v21, v65
	v_mov_b32_e32 v22, v66
	v_mov_b32_e32 v23, v67
	v_mov_b32_e32 v24, v68
	v_mov_b32_e32 v25, v69
	v_mov_b32_e32 v26, v70
	v_mov_b32_e32 v27, v71
	v_mov_b32_e32 v28, v72
	v_mov_b32_e32 v29, v73
	v_mov_b32_e32 v30, v74
	v_mov_b32_e32 v31, v75
	global_load_dwordx4 v[76:79], v12, s[14:15]
	global_load_dwordx4 v[80:83], v13, s[14:15]
	global_load_dwordx4 v[84:87], v14, s[14:15]
	global_load_dwordx4 v[88:91], v15, s[14:15]
	global_load_dwordx4 v[92:95], v12, s[12:13]
	global_load_dwordx4 v[96:99], v12, s[12:13] offset:1024
	global_load_dwordx4 v[100:103], v12, s[12:13] offset:2048
	global_load_dwordx4 v[104:107], v12, s[12:13] offset:3072
	v_lshl_add_u64 v[124:125], v[0:1], 0, s[2:3]
	global_load_dwordx4 v[60:63], v[124:125], off
	global_load_dwordx4 v[64:67], v[124:125], off offset:1024
	global_load_dwordx4 v[68:71], v[124:125], off offset:2048
	global_load_dwordx4 v[72:75], v[124:125], off offset:3072
	v_mov_b32_e32 v46, v17
	v_mov_b32_e32 v47, v21
	v_mov_b32_e32 v44, v16
	v_mov_b32_e32 v45, v20
	v_mov_b32_e32 v54, v25
	v_mov_b32_e32 v55, v29
	v_pk_mul_f32 v[46:47], v[46:47], v[46:47]
	v_mov_b32_e32 v48, v18
	v_mov_b32_e32 v49, v22
	v_mov_b32_e32 v52, v24
	v_mov_b32_e32 v53, v28
	v_pk_mul_f32 v[54:55], v[54:55], v[54:55]
	v_pk_fma_f32 v[44:45], v[44:45], v[44:45], v[46:47]
	v_mov_b32_e32 v50, v19
	v_mov_b32_e32 v51, v23
	v_mov_b32_e32 v56, v26
	v_mov_b32_e32 v57, v30
	v_pk_fma_f32 v[46:47], v[52:53], v[52:53], v[54:55]
	v_pk_fma_f32 v[44:45], v[48:49], v[48:49], v[44:45]
	v_mov_b32_e32 v58, v27
	v_mov_b32_e32 v59, v31
	v_pk_fma_f32 v[46:47], v[56:57], v[56:57], v[46:47]
	v_pk_fma_f32 v[44:45], v[50:51], v[50:51], v[44:45]
	v_pk_fma_f32 v[46:47], v[58:59], v[58:59], v[46:47]
	v_add_f32_e32 v44, v44, v45
	v_add_f32_e32 v44, v44, v46
	v_add_f32_e32 v44, v44, v47
	ds_bpermute_b32 v45, v6, v44
	s_waitcnt lgkmcnt(0)
	v_add_f32_e32 v44, v44, v45
	ds_bpermute_b32 v45, v7, v44
	s_waitcnt lgkmcnt(0)
	v_add_f32_e32 v44, v44, v45
	ds_bpermute_b32 v45, v8, v44
	s_waitcnt lgkmcnt(0)
	v_add_f32_e32 v44, v44, v45
	ds_bpermute_b32 v45, v9, v44
	s_waitcnt lgkmcnt(0)
	v_add_f32_e32 v44, v44, v45
	ds_bpermute_b32 v45, v10, v44
	s_waitcnt lgkmcnt(0)
	v_add_f32_e32 v46, v44, v45
	ds_bpermute_b32 v47, v11, v46
	v_lshl_add_u64 v[44:45], v[4:5], 0, s[16:17]
	s_waitcnt lgkmcnt(0)
	v_add_f32_e32 v46, v46, v47
	v_fmamk_f32 v46, v46, 0x3a800000, v182
	v_mul_f32_e32 v47, 0x4b800000, v46
	v_cmp_gt_f32_e32 vcc, s56, v46
	s_nop 1
	v_cndmask_b32_e32 v46, v46, v47, vcc
	v_rsq_f32_e32 v46, v46
	s_nop 0
	v_mul_f32_e32 v47, 0x45800000, v46
	v_cndmask_b32_e32 v46, v46, v47, vcc
	s_waitcnt vmcnt(4)
	v_mul_f32_e32 v48, v16, v46
	v_mul_f32_e32 v49, v17, v46
	v_mul_f32_e32 v50, v18, v46
	v_mul_f32_e32 v51, v19, v46
	v_mul_f32_e32 v48, v108, v48
	v_mul_f32_e32 v49, v109, v49
	v_mul_f32_e32 v50, v110, v50
	v_mul_f32_e32 v51, v111, v51
	v_add_f32_e32 v52, 1.0, v76
	v_add_f32_e32 v53, 1.0, v77
	v_add_f32_e32 v54, 1.0, v78
	v_add_f32_e32 v55, 1.0, v79
	v_fma_f32 v48, v48, v52, v92
	v_fma_f32 v49, v49, v53, v93
	v_fma_f32 v50, v50, v54, v94
	v_fma_f32 v51, v51, v55, v95
	v_cvt_pk_bf16_f32 v32, v48, v49
	v_cvt_pk_bf16_f32 v33, v50, v51
	global_store_dwordx2 v[44:45], v[32:33], off
	v_mul_f32_e32 v48, v20, v46
	v_mul_f32_e32 v49, v21, v46
	v_mul_f32_e32 v50, v22, v46
	v_mul_f32_e32 v51, v23, v46
	v_mul_f32_e32 v48, v112, v48
	v_mul_f32_e32 v49, v113, v49
	v_mul_f32_e32 v50, v114, v50
	v_mul_f32_e32 v51, v115, v51
	v_add_f32_e32 v52, 1.0, v80
	v_add_f32_e32 v53, 1.0, v81
	v_add_f32_e32 v54, 1.0, v82
	v_add_f32_e32 v55, 1.0, v83
	v_fma_f32 v48, v48, v52, v96
	v_fma_f32 v49, v49, v53, v97
	v_fma_f32 v50, v50, v54, v98
	v_fma_f32 v51, v51, v55, v99
	v_cvt_pk_bf16_f32 v34, v48, v49
	v_cvt_pk_bf16_f32 v35, v50, v51
	global_store_dwordx2 v[44:45], v[34:35], off offset:512
	v_mul_f32_e32 v48, v24, v46
	v_mul_f32_e32 v49, v25, v46
	v_mul_f32_e32 v50, v26, v46
	v_mul_f32_e32 v51, v27, v46
	v_mul_f32_e32 v48, v116, v48
	v_mul_f32_e32 v49, v117, v49
	v_mul_f32_e32 v50, v118, v50
	v_mul_f32_e32 v51, v119, v51
	v_add_f32_e32 v52, 1.0, v84
	v_add_f32_e32 v53, 1.0, v85
	v_add_f32_e32 v54, 1.0, v86
	v_add_f32_e32 v55, 1.0, v87
	v_fma_f32 v48, v48, v52, v100
	v_fma_f32 v49, v49, v53, v101
	v_fma_f32 v50, v50, v54, v102
	v_fma_f32 v51, v51, v55, v103
	v_cvt_pk_bf16_f32 v36, v48, v49
	v_cvt_pk_bf16_f32 v37, v50, v51
	global_store_dwordx2 v[44:45], v[36:37], off offset:1024
	v_mul_f32_e32 v48, v28, v46
	v_mul_f32_e32 v49, v29, v46
	v_mul_f32_e32 v50, v30, v46
	v_mul_f32_e32 v51, v31, v46
	v_mul_f32_e32 v48, v120, v48
	v_mul_f32_e32 v49, v121, v49
	v_mul_f32_e32 v50, v122, v50
	v_mul_f32_e32 v51, v123, v51
	v_add_f32_e32 v52, 1.0, v88
	v_add_f32_e32 v53, 1.0, v89
	v_add_f32_e32 v54, 1.0, v90
	v_add_f32_e32 v55, 1.0, v91
	v_fma_f32 v48, v48, v52, v104
	v_fma_f32 v49, v49, v53, v105
	v_fma_f32 v50, v50, v54, v106
	v_fma_f32 v51, v51, v55, v107
	v_cvt_pk_bf16_f32 v38, v48, v49
	v_cvt_pk_bf16_f32 v39, v50, v51
	global_store_dwordx2 v[44:45], v[38:39], off offset:1536
	s_mov_b32 s8, s32
	s_cmp_gt_i32 s8, s18
	s_cbranch_scc0 .Ldp1_loop
